# static s_setprio 1 for waves 4-7 during the P5 mixer work-queue loop (younger-half priority raise)
# baseline (speedup 1.0000x reference)
; #define PH_BEGIN const int tid = otid(); const int G = gridDim.x; const int bid = osi((int)blockIdx.x); unsigned char* ws = osp(P.ws); float* out = osp(P.out); unsigned char* U = ws + WS_U; (void)tid; (void)G; (void)bid; (void)out; (void)U;
; __global__ void __launch_bounds__(512, 2) mega(Params P) {
;     ...
;             for (int rep = 0; rep < REP_P5; ++rep)
;             for (;;) {
;                 PH_BEGIN
;                 __syncthreads();
;                 if (tid == 0) *sitem = (int)atomicAdd(WSP(unsigned, WS_CTL) + 3600 + l + 2 * rep, 1u);
;                 __syncthreads();
;                 const int it = *sitem;
;                 if (it >= 1280) break;
.LBB0_889:
	s_cmp_lt_u32 s21, 4
	s_cbranch_scc1 .Lprio_p5
	s_setprio 1
